# P4 compress item: the five strided row loads of the LDS fill issued together with one wait (was one load round trip per element)
# baseline (speedup 1.0000x reference)
.LBB0_628:
	s_cmp_gt_i32 s4, 31
	s_mov_b64 s[2:3], -1
	s_movk_i32 s24, 0x90
	s_mov_b64 s[34:35], 0x100
	s_cbranch_scc0 .LBB0_646
	s_sub_i32 s19, s4, 32
	v_mov_b32_e32 v24, v220
	s_load_dwordx2 s[6:7], s[0:1], 0x98
	s_lshl_b32 s2, s19, 4
	s_bfe_u32 s18, s19, 0x30004
	s_and_b32 s5, s2, 0xf0
	s_cmpk_lt_u32 s19, 0x80
	s_cselect_b64 s[8:9], -1, 0
	s_cmpk_gt_u32 s19, 0x7f
	s_movk_i32 s10, 0x880
	s_cselect_b64 s[2:3], -1, 0
	v_cmp_gt_i32_e32 vcc, s10, v24
	s_and_saveexec_b64 s[10:11], vcc
	s_cbranch_execz .LBB0_634
	s_lshl_b32 s20, s5, 4
	s_and_b64 s[12:13], s[8:9], exec
	s_movk_i32 s12, 0x880
	s_cselect_b32 s12, 0x800, s12
	s_waitcnt lgkmcnt(0)
	s_add_u32 s12, s6, s12
	v_lshlrev_b32_e32 v0, 4, v24
	s_addc_u32 s13, s7, 0
	v_and_b32_e32 v0, 0x70, v0
	v_lshl_add_u64 v[2:3], s[12:13], 0, v[0:1]
	s_mov_b64 s[12:13], 0x5600000
	s_lshl_b32 s21, s18, 12
	v_lshl_add_u64 v[6:7], v[2:3], 0, s[12:13]
	v_add_u32_e32 v0, 0, v0
	s_mov_b64 s[12:13], 0
	v_mov_b32_e32 v8, v24
	v_add_u32_e32 v8, 0x0, v24
	v_ashrrev_i32_e32 v2, 3, v8
	v_add_u32_e32 v9, s20, v2
	v_mov_b32_e32 v44, 0
	v_mov_b32_e32 v45, 0
	v_mov_b32_e32 v46, 0
	v_mov_b32_e32 v47, 0
	v_bfe_u32 v60, v8, 3, 4
	v_ashrrev_i32_e32 v61, 7, v8
	v_mad_u32_u24 v60, v60, 17, v61
	v_mad_u64_u32 v[70:71], vcc, v60, s24, v[0:1]
	s_movk_i32 s14, 0x1000
	v_cmp_gt_i32_e32 vcc, s14, v9
	s_and_saveexec_b64 s[14:15], vcc
	v_add_u32_e32 v2, s21, v9
	v_mad_i64_i32 v[2:3], s[22:23], v2, s64, v[6:7]
	global_load_dwordx4 v[44:47], v[2:3], off
	s_mov_b64 exec, s[14:15]
	v_add_u32_e32 v8, 0x200, v24
	v_ashrrev_i32_e32 v2, 3, v8
	v_add_u32_e32 v9, s20, v2
	v_mov_b32_e32 v48, 0
	v_mov_b32_e32 v49, 0
	v_mov_b32_e32 v50, 0
	v_mov_b32_e32 v51, 0
	v_bfe_u32 v60, v8, 3, 4
	v_ashrrev_i32_e32 v61, 7, v8
	v_mad_u32_u24 v60, v60, 17, v61
	v_mad_u64_u32 v[72:73], vcc, v60, s24, v[0:1]
	s_movk_i32 s14, 0x1000
	v_cmp_gt_i32_e32 vcc, s14, v9
	s_and_saveexec_b64 s[14:15], vcc
	v_add_u32_e32 v2, s21, v9
	v_mad_i64_i32 v[2:3], s[22:23], v2, s64, v[6:7]
	global_load_dwordx4 v[48:51], v[2:3], off
	s_mov_b64 exec, s[14:15]
	v_add_u32_e32 v8, 0x400, v24
	v_ashrrev_i32_e32 v2, 3, v8
	v_add_u32_e32 v9, s20, v2
	v_mov_b32_e32 v52, 0
	v_mov_b32_e32 v53, 0
	v_mov_b32_e32 v54, 0
	v_mov_b32_e32 v55, 0
	v_bfe_u32 v60, v8, 3, 4
	v_ashrrev_i32_e32 v61, 7, v8
	v_mad_u32_u24 v60, v60, 17, v61
	v_mad_u64_u32 v[74:75], vcc, v60, s24, v[0:1]
	s_movk_i32 s14, 0x1000
	v_cmp_gt_i32_e32 vcc, s14, v9
	s_and_saveexec_b64 s[14:15], vcc
	v_add_u32_e32 v2, s21, v9
	v_mad_i64_i32 v[2:3], s[22:23], v2, s64, v[6:7]
	global_load_dwordx4 v[52:55], v[2:3], off
	s_mov_b64 exec, s[14:15]
	v_add_u32_e32 v8, 0x600, v24
	v_ashrrev_i32_e32 v2, 3, v8
	v_add_u32_e32 v9, s20, v2
	v_mov_b32_e32 v56, 0
	v_mov_b32_e32 v57, 0
	v_mov_b32_e32 v58, 0
	v_mov_b32_e32 v59, 0
	v_bfe_u32 v60, v8, 3, 4
	v_ashrrev_i32_e32 v61, 7, v8
	v_mad_u32_u24 v60, v60, 17, v61
	v_mad_u64_u32 v[76:77], vcc, v60, s24, v[0:1]
	s_movk_i32 s14, 0x1000
	v_cmp_gt_i32_e32 vcc, s14, v9
	s_and_saveexec_b64 s[14:15], vcc
	v_add_u32_e32 v2, s21, v9
	v_mad_i64_i32 v[2:3], s[22:23], v2, s64, v[6:7]
	global_load_dwordx4 v[56:59], v[2:3], off
	s_mov_b64 exec, s[14:15]
	v_cmp_gt_i32_e32 vcc, 0x80, v24
	s_and_saveexec_b64 s[12:13], vcc
	v_add_u32_e32 v8, 0x800, v24
	v_ashrrev_i32_e32 v2, 3, v8
	v_add_u32_e32 v9, s20, v2
	v_mov_b32_e32 v60, 0
	v_mov_b32_e32 v61, 0
	v_mov_b32_e32 v62, 0
	v_mov_b32_e32 v63, 0
	v_bfe_u32 v60, v8, 3, 4
	v_ashrrev_i32_e32 v61, 7, v8
	v_mad_u32_u24 v60, v60, 17, v61
	v_mad_u64_u32 v[78:79], vcc, v60, s24, v[0:1]
	s_movk_i32 s14, 0x1000
	v_cmp_gt_i32_e32 vcc, s14, v9
	s_and_saveexec_b64 s[14:15], vcc
	v_add_u32_e32 v2, s21, v9
	v_mad_i64_i32 v[2:3], s[22:23], v2, s64, v[6:7]
	global_load_dwordx4 v[60:63], v[2:3], off
	s_mov_b64 exec, s[14:15]
	s_waitcnt vmcnt(0)
	ds_write_b128 v78, v[60:63]
	s_mov_b64 exec, s[12:13]
	ds_write_b128 v70, v[44:47]
	ds_write_b128 v72, v[48:51]
	ds_write_b128 v74, v[52:55]
	ds_write_b128 v76, v[56:59]
